# v27 plus: sample-row GEMMs of P3 and P4 issue all operand loads and their epilogue loads up front (one memory round trip instead of three)
# speedup vs baseline: 1.0011x; 1.0011x over previous
; #define LAS __attribute__((address_space(3)))
; __device__ __forceinline__ float bf_lo(unsigned u) { return __uint_as_float(u << 16); }
; template <bool GATED>
; __device__ __forceinline__ void sample_gemm(LAS unsigned char* lds, const bf16_t* A, const bf16_t* WT, const bf16_t* GSg, const bf16_t* GCg, bf16_t* Hout,
;                                             const float* xs, float* yout, int j, int wave, int lane, int tid) {
;     ...
;     const int row0 = MP + 32 * (j & 15), col0 = 64 * (j >> 4);
;     const bf16_t* ap = A + (size_t)(row0 + r32) * 1024 + wave * 128 + hi * 8;
;     const bf16_t* bp0 = WT + (size_t)prow(col0 + r32) * 1024 + wave * 128 + hi * 8;
;     const bf16_t* bp1 = WT + (size_t)prow(col0 + 32 + r32) * 1024 + wave * 128 + hi * 8;
;     f32x16 c0 = {}, c1 = {};
; #pragma unroll
;     for (int ks = 0; ks < 8; ++ks) { const bf16x8 a = *(const bf16x8*)(ap + 16 * ks), b0 = *(const bf16x8*)(bp0 + 16 * ks), b1 = *(const bf16x8*)(bp1 + 16 * ks);
;         c0 = __builtin_amdgcn_mfma_f32_32x32x16_bf16(a, b0, c0, 0, 0, 0); c1 = __builtin_amdgcn_mfma_f32_32x32x16_bf16(a, b1, c1, 0, 0, 0); }
;     LAS float* pl = (LAS float*)lds + wave * 2048;
; #pragma unroll
;     for (int r = 0; r < 16; ++r) { const int rr = (r & 3) + 8 * (r >> 2) + 4 * hi; pl[rr * 64 + r32] = c0[r]; pl[rr * 64 + 32 + r32] = c1[r]; }
;     __syncthreads();
;     { const int row = tid >> 4, cq = (tid & 15) * 4; const LAS float* q = (const LAS float*)lds + row * 64 + cq;
;       f32x4 sb = *(const LAS f32x4*)(q) + *(const LAS f32x4*)(q + 2048) + *(const LAS f32x4*)(q + 4096) + *(const LAS f32x4*)(q + 6144);
;       f32x4 cb = *(const LAS f32x4*)(q + 8192) + *(const LAS f32x4*)(q + 10240) + *(const LAS f32x4*)(q + 12288) + *(const LAS f32x4*)(q + 14336);
;       const size_t off = (size_t)(row0 + row) * 1024 + col0 + cq;
;       if (GATED) { const u32x2 a = *(const u32x2*)(GSg + off), c = *(const u32x2*)(GCg + off);
;           u32x2 w; w.x = cvt_pk_bf16(sb[0] * bf_lo(a.x) + cb[0] * bf_lo(c.x), sb[1] * bf_hi(a.x) + cb[1] * bf_hi(c.x)); w.y = cvt_pk_bf16(sb[2] * bf_lo(a.y) + cb[2] * bf_lo(c.y), sb[3] * bf_hi(a.y) + cb[3] * bf_hi(c.y));
;           *(u32x2*)(Hout + off) = w; }
;       else { const f32x4 x = *(const f32x4*)(xs + off - (size_t)MP * 1024); *(f32x4*)(yout + off) = x + sb + cb; } }
;     __syncthreads();
.LBB0_497:
	s_and_b32 s13, s8, 0x1e0
	s_and_b32 s6, s10, 0xffffffc0
	s_bitset1_b32 s13, 15
	v_or_b32_e32 v0, s6, v40
	v_or_b32_e32 v1, s6, v39
	v_or_b32_e32 v4, s13, v40
	v_lshrrev_b32_e32 v0, 1, v0
	v_bitop3_b32 v2, s6, v62, v40 bitop3:0xc8
	v_lshrrev_b32_e32 v1, 1, v1
	v_lshlrev_b32_e32 v32, 11, v4
	v_and_b32_e32 v4, 0x6c, v0
	v_bitop3_b32 v3, s6, v62, v39 bitop3:0xc8
	v_and_b32_e32 v5, 0x6c, v1
	v_or3_b32 v2, v2, v4, v41
	v_lshl_add_u64 v[0:1], v[34:35], 0, v[32:33]
	v_or3_b32 v4, v3, v5, v61
	v_ashrrev_i32_e32 v3, 31, v2
	v_ashrrev_i32_e32 v5, 31, v4
	global_load_dwordx4 v[16:19], v[0:1], off
	global_load_dwordx4 v[176:179], v[0:1], off offset:32
	global_load_dwordx4 v[180:183], v[0:1], off offset:64
	global_load_dwordx4 v[184:187], v[0:1], off offset:96
	global_load_dwordx4 v[76:79], v[0:1], off offset:128
	global_load_dwordx4 v[80:83], v[0:1], off offset:160
	global_load_dwordx4 v[84:87], v[0:1], off offset:192
	global_load_dwordx4 v[88:91], v[0:1], off offset:224
	v_lshlrev_b64 v[0:1], 11, v[2:3]
	v_lshlrev_b64 v[2:3], 11, v[4:5]
	v_lshl_add_u64 v[104:105], v[36:37], 0, v[0:1]
	v_lshl_add_u64 v[106:107], v[36:37], 0, v[2:3]
	global_load_dwordx4 v[0:3], v[104:105], off
	global_load_dwordx4 v[20:23], v[106:107], off
	global_load_dwordx4 v[120:123], v[104:105], off offset:32
	global_load_dwordx4 v[148:151], v[106:107], off offset:32
	global_load_dwordx4 v[124:127], v[104:105], off offset:64
	global_load_dwordx4 v[152:155], v[106:107], off offset:64
	global_load_dwordx4 v[128:131], v[104:105], off offset:96
	global_load_dwordx4 v[156:159], v[106:107], off offset:96
	global_load_dwordx4 v[132:135], v[104:105], off offset:128
	global_load_dwordx4 v[160:163], v[106:107], off offset:128
	global_load_dwordx4 v[136:139], v[104:105], off offset:160
	global_load_dwordx4 v[164:167], v[106:107], off offset:160
	global_load_dwordx4 v[140:143], v[104:105], off offset:192
	global_load_dwordx4 v[168:171], v[106:107], off offset:192
	global_load_dwordx4 v[144:147], v[104:105], off offset:224
	global_load_dwordx4 v[172:175], v[106:107], off offset:224
	s_ashr_i32 s7, s6, 31
	v_add_u32_e32 v72, s13, v59
	v_ashrrev_i32_e32 v73, 31, v72
	v_lshlrev_b64 v[68:69], 10, v[72:73]
	v_lshl_add_u64 v[68:69], v[68:69], 0, s[6:7]
	v_or_b32_e32 v68, v68, v38
	v_lshlrev_b64 v[68:69], 1, v[68:69]
	v_lshl_add_u64 v[70:71], s[56:57], 0, v[68:69]
	v_lshl_add_u64 v[72:73], s[4:5], 0, v[68:69]
	v_lshl_add_u64 v[68:69], s[58:59], 0, v[68:69]
	global_load_dwordx2 v[64:65], v[70:71], off
	global_load_dwordx2 v[66:67], v[72:73], off
	s_add_i32 s12, s12, s3
	s_add_i32 s8, s8, s9
	s_add_i32 s10, s10, s11
	s_cmpk_gt_i32 s12, 0xff
	s_waitcnt vmcnt(17)
	v_mfma_f32_32x32x16_bf16 v[0:15], v[16:19], v[0:3], 0
	s_waitcnt vmcnt(16)
	v_mfma_f32_32x32x16_bf16 v[16:31], v[16:19], v[20:23], 0
	s_waitcnt vmcnt(15)
	v_mfma_f32_32x32x16_bf16 v[0:15], v[176:179], v[120:123], v[0:15]
	s_waitcnt vmcnt(14)
	v_mfma_f32_32x32x16_bf16 v[16:31], v[176:179], v[148:151], v[16:31]
	s_waitcnt vmcnt(13)
	v_mfma_f32_32x32x16_bf16 v[0:15], v[180:183], v[124:127], v[0:15]
	s_waitcnt vmcnt(12)
	v_mfma_f32_32x32x16_bf16 v[16:31], v[180:183], v[152:155], v[16:31]
	s_waitcnt vmcnt(11)
	v_mfma_f32_32x32x16_bf16 v[0:15], v[184:187], v[128:131], v[0:15]
	s_waitcnt vmcnt(10)
	v_mfma_f32_32x32x16_bf16 v[16:31], v[184:187], v[156:159], v[16:31]
	s_waitcnt vmcnt(9)
	v_mfma_f32_32x32x16_bf16 v[0:15], v[76:79], v[132:135], v[0:15]
	s_waitcnt vmcnt(8)
	v_mfma_f32_32x32x16_bf16 v[16:31], v[76:79], v[160:163], v[16:31]
	s_waitcnt vmcnt(7)
	v_mfma_f32_32x32x16_bf16 v[0:15], v[80:83], v[136:139], v[0:15]
	s_waitcnt vmcnt(6)
	v_mfma_f32_32x32x16_bf16 v[16:31], v[80:83], v[164:167], v[16:31]
	s_waitcnt vmcnt(5)
	v_mfma_f32_32x32x16_bf16 v[0:15], v[84:87], v[140:143], v[0:15]
	s_waitcnt vmcnt(4)
	v_mfma_f32_32x32x16_bf16 v[16:31], v[84:87], v[168:171], v[16:31]
	s_waitcnt vmcnt(3)
	v_mfma_f32_32x32x16_bf16 v[0:15], v[88:91], v[144:147], v[0:15]
	s_waitcnt vmcnt(2)
	v_mfma_f32_32x32x16_bf16 v[16:31], v[88:91], v[172:175], v[16:31]
	s_nop 7
	s_nop 2
	ds_write_b32 v42, v0
	s_nop 7
	ds_write_b32 v43, v16
	ds_write_b32 v42, v1 offset:256
	ds_write_b32 v44, v17
	ds_write_b32 v42, v2 offset:512
	ds_write_b32 v45, v18
	ds_write_b32 v42, v3 offset:768
	ds_write_b32 v46, v19
	ds_write_b32 v42, v4 offset:2048
	ds_write_b32 v47, v20
	ds_write_b32 v42, v5 offset:2304
	ds_write_b32 v48, v21
	ds_write_b32 v42, v6 offset:2560
	ds_write_b32 v49, v22
	ds_write_b32 v42, v7 offset:2816
	ds_write_b32 v50, v23
	ds_write_b32 v42, v8 offset:4096
	ds_write_b32 v51, v24
	ds_write_b32 v42, v9 offset:4352
	ds_write_b32 v52, v25
	ds_write_b32 v42, v10 offset:4608
	ds_write_b32 v53, v26
	ds_write_b32 v42, v11 offset:4864
	ds_write_b32 v54, v27
	ds_write_b32 v42, v12 offset:6144
	ds_write_b32 v55, v28
	ds_write_b32 v42, v13 offset:6400
	ds_write_b32 v56, v29
	ds_write_b32 v42, v14 offset:6656
	ds_write_b32 v57, v30
	ds_write_b32 v42, v15 offset:6912
	ds_write_b32 v58, v31
	s_waitcnt lgkmcnt(0)
	s_barrier
	ds_read_b128 v[0:3], v60
	ds_read_b128 v[4:7], v60 offset:8192
	ds_read_b128 v[8:11], v60 offset:16384
	ds_read_b128 v[12:15], v60 offset:24576
	ds_read_b128 v[16:19], v60 offset:32768
	ds_read_b128 v[20:23], v60 offset:40960
	ds_read_b128 v[24:27], v60 offset:49152
	ds_read_b128 v[28:31], v60 offset:57344
	s_waitcnt lgkmcnt(6)
	v_pk_add_f32 v[2:3], v[2:3], v[6:7]
	v_pk_add_f32 v[0:1], v[0:1], v[4:5]
	s_waitcnt lgkmcnt(2)
	v_pk_add_f32 v[4:5], v[18:19], v[22:23]
	v_pk_add_f32 v[6:7], v[16:17], v[20:21]
	v_pk_add_f32 v[2:3], v[2:3], v[10:11]
	s_waitcnt lgkmcnt(1)
	v_pk_add_f32 v[4:5], v[4:5], v[26:27]
	v_pk_add_f32 v[6:7], v[6:7], v[24:25]
	v_pk_add_f32 v[0:1], v[0:1], v[8:9]
	v_pk_add_f32 v[2:3], v[2:3], v[14:15]
	s_waitcnt lgkmcnt(0)
	v_pk_add_f32 v[4:5], v[4:5], v[30:31]
	v_pk_add_f32 v[6:7], v[6:7], v[28:29]
	v_pk_add_f32 v[0:1], v[0:1], v[12:13]
	s_waitcnt vmcnt(1)
	v_lshlrev_b32_e32 v8, 16, v64
	s_waitcnt vmcnt(0)
	v_lshlrev_b32_e32 v10, 16, v66
	v_and_b32_e32 v11, 0xffff0000, v66
	v_lshlrev_b32_e32 v14, 16, v67
	v_and_b32_e32 v15, 0xffff0000, v67
	v_and_b32_e32 v9, 0xffff0000, v64
	v_lshlrev_b32_e32 v12, 16, v65
	v_and_b32_e32 v13, 0xffff0000, v65
	v_pk_mul_f32 v[6:7], v[6:7], v[10:11]
	v_pk_mul_f32 v[4:5], v[4:5], v[14:15]
	v_pk_fma_f32 v[0:1], v[0:1], v[8:9], v[6:7]
	v_pk_fma_f32 v[2:3], v[2:3], v[12:13], v[4:5]
	v_cvt_pk_bf16_f32 v0, v0, v1
	v_cvt_pk_bf16_f32 v1, v2, v3
	global_store_dwordx2 v[68:69], v[0:1], off
	s_barrier
	s_cbranch_scc0 .LBB0_497

; #define LAS __attribute__((address_space(3)))
; __device__ __forceinline__ float bf_lo(unsigned u) { return __uint_as_float(u << 16); }
; template <bool GATED>
; __device__ __forceinline__ void sample_gemm(LAS unsigned char* lds, const bf16_t* A, const bf16_t* WT, const bf16_t* GSg, const bf16_t* GCg, bf16_t* Hout,
;                                             const float* xs, float* yout, int j, int wave, int lane, int tid) {
;     ...
;     const int row0 = MP + 32 * (j & 15), col0 = 64 * (j >> 4);
;     const bf16_t* ap = A + (size_t)(row0 + r32) * 1024 + wave * 128 + hi * 8;
;     const bf16_t* bp0 = WT + (size_t)prow(col0 + r32) * 1024 + wave * 128 + hi * 8;
;     const bf16_t* bp1 = WT + (size_t)prow(col0 + 32 + r32) * 1024 + wave * 128 + hi * 8;
;     f32x16 c0 = {}, c1 = {};
; #pragma unroll
;     for (int ks = 0; ks < 8; ++ks) { const bf16x8 a = *(const bf16x8*)(ap + 16 * ks), b0 = *(const bf16x8*)(bp0 + 16 * ks), b1 = *(const bf16x8*)(bp1 + 16 * ks);
;         c0 = __builtin_amdgcn_mfma_f32_32x32x16_bf16(a, b0, c0, 0, 0, 0); c1 = __builtin_amdgcn_mfma_f32_32x32x16_bf16(a, b1, c1, 0, 0, 0); }
;     LAS float* pl = (LAS float*)lds + wave * 2048;
; #pragma unroll
;     for (int r = 0; r < 16; ++r) { const int rr = (r & 3) + 8 * (r >> 2) + 4 * hi; pl[rr * 64 + r32] = c0[r]; pl[rr * 64 + 32 + r32] = c1[r]; }
;     __syncthreads();
;     { const int row = tid >> 4, cq = (tid & 15) * 4; const LAS float* q = (const LAS float*)lds + row * 64 + cq;
;       f32x4 sb = *(const LAS f32x4*)(q) + *(const LAS f32x4*)(q + 2048) + *(const LAS f32x4*)(q + 4096) + *(const LAS f32x4*)(q + 6144);
;       f32x4 cb = *(const LAS f32x4*)(q + 8192) + *(const LAS f32x4*)(q + 10240) + *(const LAS f32x4*)(q + 12288) + *(const LAS f32x4*)(q + 14336);
;       const size_t off = (size_t)(row0 + row) * 1024 + col0 + cq;
;       if (GATED) { const u32x2 a = *(const u32x2*)(GSg + off), c = *(const u32x2*)(GCg + off);
;           u32x2 w; w.x = cvt_pk_bf16(sb[0] * bf_lo(a.x) + cb[0] * bf_lo(c.x), sb[1] * bf_hi(a.x) + cb[1] * bf_hi(c.x)); w.y = cvt_pk_bf16(sb[2] * bf_lo(a.y) + cb[2] * bf_lo(c.y), sb[3] * bf_hi(a.y) + cb[3] * bf_hi(c.y));
;           *(u32x2*)(Hout + off) = w; }
;       else { const f32x4 x = *(const f32x4*)(xs + off - (size_t)MP * 1024); *(f32x4*)(yout + off) = x + sb + cb; } }
;     __syncthreads();
.LBB0_584:
	s_and_b32 s10, s4, 0x1e0
	s_and_b32 s0, s6, 0xffffffc0
	s_bitset1_b32 s10, 15
	v_or_b32_e32 v0, s0, v40
	v_or_b32_e32 v1, s0, v39
	v_or_b32_e32 v4, s10, v40
	v_lshrrev_b32_e32 v0, 1, v0
	v_bitop3_b32 v2, s0, v62, v40 bitop3:0xc8
	v_lshrrev_b32_e32 v1, 1, v1
	v_lshlrev_b32_e32 v32, 11, v4
	v_and_b32_e32 v4, 0x6c, v0
	v_bitop3_b32 v3, s0, v62, v39 bitop3:0xc8
	v_and_b32_e32 v5, 0x6c, v1
	v_or3_b32 v2, v2, v4, v41
	v_lshl_add_u64 v[0:1], v[34:35], 0, v[32:33]
	v_or3_b32 v4, v3, v5, v61
	v_ashrrev_i32_e32 v3, 31, v2
	v_ashrrev_i32_e32 v5, 31, v4
	global_load_dwordx4 v[16:19], v[0:1], off
	global_load_dwordx4 v[176:179], v[0:1], off offset:32
	global_load_dwordx4 v[180:183], v[0:1], off offset:64
	global_load_dwordx4 v[184:187], v[0:1], off offset:96
	global_load_dwordx4 v[76:79], v[0:1], off offset:128
	global_load_dwordx4 v[80:83], v[0:1], off offset:160
	global_load_dwordx4 v[84:87], v[0:1], off offset:192
	global_load_dwordx4 v[88:91], v[0:1], off offset:224
	v_lshlrev_b64 v[0:1], 11, v[2:3]
	v_lshlrev_b64 v[2:3], 11, v[4:5]
	v_lshl_add_u64 v[104:105], v[36:37], 0, v[0:1]
	v_lshl_add_u64 v[106:107], v[36:37], 0, v[2:3]
	global_load_dwordx4 v[0:3], v[104:105], off
	global_load_dwordx4 v[20:23], v[106:107], off
	global_load_dwordx4 v[120:123], v[104:105], off offset:32
	global_load_dwordx4 v[148:151], v[106:107], off offset:32
	global_load_dwordx4 v[124:127], v[104:105], off offset:64
	global_load_dwordx4 v[152:155], v[106:107], off offset:64
	global_load_dwordx4 v[128:131], v[104:105], off offset:96
	global_load_dwordx4 v[156:159], v[106:107], off offset:96
	global_load_dwordx4 v[132:135], v[104:105], off offset:128
	global_load_dwordx4 v[160:163], v[106:107], off offset:128
	global_load_dwordx4 v[136:139], v[104:105], off offset:160
	global_load_dwordx4 v[164:167], v[106:107], off offset:160
	global_load_dwordx4 v[140:143], v[104:105], off offset:192
	global_load_dwordx4 v[168:171], v[106:107], off offset:192
	global_load_dwordx4 v[144:147], v[104:105], off offset:224
	global_load_dwordx4 v[172:175], v[106:107], off offset:224
	s_ashr_i32 s1, s0, 31
	s_add_i32 s9, s9, s3
	s_add_i32 s4, s4, s5
	s_add_i32 s6, s6, s7
	s_cmpk_gt_i32 s9, 0xff
	v_add_u32_e32 v72, s10, v59
	v_ashrrev_i32_e32 v73, 31, v72
	v_lshlrev_b64 v[72:73], 10, v[72:73]
	v_lshl_add_u64 v[72:73], v[72:73], 0, s[0:1]
	v_or_b32_e32 v72, v72, v38
	v_lshlrev_b64 v[68:69], 2, v[72:73]
	s_waitcnt lgkmcnt(0)
	v_lshl_add_u64 v[70:71], s[66:67], 0, v[68:69]
	v_add_co_u32_e32 v70, vcc, s8, v70
	v_lshl_add_u64 v[68:69], s[60:61], 0, v[68:69]
	s_nop 0
	v_addc_co_u32_e32 v71, vcc, -1, v71, vcc
	s_nop 0
	global_load_dwordx4 v[112:115], v[70:71], off
	s_waitcnt vmcnt(16)
	v_mfma_f32_32x32x16_bf16 v[0:15], v[16:19], v[0:3], 0
	s_waitcnt vmcnt(15)
	v_mfma_f32_32x32x16_bf16 v[16:31], v[16:19], v[20:23], 0
	s_waitcnt vmcnt(14)
	v_mfma_f32_32x32x16_bf16 v[0:15], v[176:179], v[120:123], v[0:15]
	s_waitcnt vmcnt(13)
	v_mfma_f32_32x32x16_bf16 v[16:31], v[176:179], v[148:151], v[16:31]
	s_waitcnt vmcnt(12)
	v_mfma_f32_32x32x16_bf16 v[0:15], v[180:183], v[124:127], v[0:15]
	s_waitcnt vmcnt(11)
	v_mfma_f32_32x32x16_bf16 v[16:31], v[180:183], v[152:155], v[16:31]
	s_waitcnt vmcnt(10)
	v_mfma_f32_32x32x16_bf16 v[0:15], v[184:187], v[128:131], v[0:15]
	s_waitcnt vmcnt(9)
	v_mfma_f32_32x32x16_bf16 v[16:31], v[184:187], v[156:159], v[16:31]
	s_waitcnt vmcnt(8)
	v_mfma_f32_32x32x16_bf16 v[0:15], v[76:79], v[132:135], v[0:15]
	s_waitcnt vmcnt(7)
	v_mfma_f32_32x32x16_bf16 v[16:31], v[76:79], v[160:163], v[16:31]
	s_waitcnt vmcnt(6)
	v_mfma_f32_32x32x16_bf16 v[0:15], v[80:83], v[136:139], v[0:15]
	s_waitcnt vmcnt(5)
	v_mfma_f32_32x32x16_bf16 v[16:31], v[80:83], v[164:167], v[16:31]
	s_waitcnt vmcnt(4)
	v_mfma_f32_32x32x16_bf16 v[0:15], v[84:87], v[140:143], v[0:15]
	s_waitcnt vmcnt(3)
	v_mfma_f32_32x32x16_bf16 v[16:31], v[84:87], v[168:171], v[16:31]
	s_waitcnt vmcnt(2)
	v_mfma_f32_32x32x16_bf16 v[0:15], v[88:91], v[144:147], v[0:15]
	s_waitcnt vmcnt(1)
	v_mfma_f32_32x32x16_bf16 v[16:31], v[88:91], v[172:175], v[16:31]
	s_nop 7
	s_nop 2
	ds_write_b32 v42, v0
	s_nop 7
	ds_write_b32 v43, v16
	ds_write_b32 v42, v1 offset:256
	ds_write_b32 v44, v17
	ds_write_b32 v42, v2 offset:512
	ds_write_b32 v45, v18
	ds_write_b32 v42, v3 offset:768
	ds_write_b32 v46, v19
	ds_write_b32 v42, v4 offset:2048
	ds_write_b32 v47, v20
	ds_write_b32 v42, v5 offset:2304
	ds_write_b32 v48, v21
	ds_write_b32 v42, v6 offset:2560
	ds_write_b32 v49, v22
	ds_write_b32 v42, v7 offset:2816
	ds_write_b32 v50, v23
	ds_write_b32 v42, v8 offset:4096
	ds_write_b32 v51, v24
	ds_write_b32 v42, v9 offset:4352
	ds_write_b32 v52, v25
	ds_write_b32 v42, v10 offset:4608
	ds_write_b32 v53, v26
	ds_write_b32 v42, v11 offset:4864
	ds_write_b32 v54, v27
	ds_write_b32 v42, v12 offset:6144
	ds_write_b32 v55, v28
	ds_write_b32 v42, v13 offset:6400
	ds_write_b32 v56, v29
	ds_write_b32 v42, v14 offset:6656
	ds_write_b32 v57, v30
	ds_write_b32 v42, v15 offset:6912
	ds_write_b32 v58, v31
	s_waitcnt lgkmcnt(0)
	s_barrier
	ds_read_b128 v[4:7], v60
	ds_read_b128 v[8:11], v60 offset:8192
	ds_read_b128 v[12:15], v60 offset:16384
	ds_read_b128 v[16:19], v60 offset:24576
	ds_read_b128 v[20:23], v60 offset:32768
	ds_read_b128 v[24:27], v60 offset:40960
	ds_read_b128 v[28:31], v60 offset:49152
	ds_read_b128 v[64:67], v60 offset:57344
	s_waitcnt lgkmcnt(6)
	v_pk_add_f32 v[6:7], v[6:7], v[10:11]
	v_pk_add_f32 v[4:5], v[4:5], v[8:9]
	s_waitcnt lgkmcnt(2)
	v_pk_add_f32 v[8:9], v[22:23], v[26:27]
	v_pk_add_f32 v[10:11], v[20:21], v[24:25]
	v_pk_add_f32 v[6:7], v[6:7], v[14:15]
	v_pk_add_f32 v[4:5], v[4:5], v[12:13]
	s_waitcnt lgkmcnt(1)
	v_pk_add_f32 v[8:9], v[8:9], v[30:31]
	v_pk_add_f32 v[10:11], v[10:11], v[28:29]
	v_pk_add_f32 v[6:7], v[6:7], v[18:19]
	v_pk_add_f32 v[4:5], v[4:5], v[16:17]
	s_waitcnt lgkmcnt(0)
	v_pk_add_f32 v[8:9], v[8:9], v[66:67]
	v_pk_add_f32 v[10:11], v[10:11], v[64:65]
	s_waitcnt vmcnt(0)
	v_pk_add_f32 v[2:3], v[6:7], v[114:115]
	v_pk_add_f32 v[0:1], v[4:5], v[112:113]
	v_pk_add_f32 v[2:3], v[8:9], v[2:3]
	v_pk_add_f32 v[0:1], v[10:11], v[0:1]
	global_store_dwordx4 v[68:69], v[0:3], off
	s_barrier
	s_cbranch_scc0 .LBB0_584
